# lru1: per-column gate parameters (lm, ba, bx) loaded at item start instead of per column group
# baseline (speedup 1.0000x reference)
; DI float softplusf_(float x) { return fmaxf(x, 0.f) + __logf(1.f + __expf(-fabsf(x))); }
; DI void lru1_item(const Params& p, int l, int it, char* smem) {
;     ...
;   const int i = tid & 63, tq = tid >> 6, ch = nb * 64 + i;
;   __syncthreads();
;   {
;     const float* cw = p.in[15] + (size_t)l * 4 * 512 + ch;
;     const float w0 = cw[0], w1 = cw[512], w2 = cw[1024], w3 = cw[1536], cb = p.in[16][(size_t)l * 512 + ch];
;     const float* buf = isS ? p.in[5] + ((size_t)l * SBT + b) * 3 * 512 + ch : nullptr;
;     float x[19];
; #pragma unroll
;     for (int j = 0; j < 19; ++j) {
;       const int tl = tq * 16 - 3 + j;
;       const int tt = t0 + tl;
;       float v = 0.f;
;       if (tl < Lc) {
;         if (tt >= 0) v = LX[(size_t)(row0 + tl) * 512 + ch];
;         else if (isS) v = buf[(3 + tt) * 512];
;       }
;       x[j] = v;
;     }
; #pragma unroll
;     for (int k = 0; k < 16; ++k) {
;       const int t = tq * 16 + k;
;       const float xv = (t < Lc) ? cb + w0 * x[k] + w1 * x[k + 1] + w2 * x[k + 2] + w3 * x[k + 3] : 0.f;
;       xcs[t * LP + i] = f2bf(xv);
;     }
; #pragma unroll
;     for (int k = 0; k < 2; ++k) {
;       const int id = tid + k * 256, r = id >> 3, c8 = id & 7;
;       *(uint4*)(was + r * LP + c8 * 8) = *(const uint4*)(Wl + W_WA + nb * 4096 + r * 64 + c8 * 8);
;       *(uint4*)(wxs + r * LP + c8 * 8) = *(const uint4*)(Wl + W_WX + nb * 4096 + r * 64 + c8 * 8);
;     }
;     ...
;     const float* ba = p.in[18] + (size_t)l * 512 + nb * 64;
;     const float* bx = p.in[20] + (size_t)l * 512 + nb * 64;
;     const float* lm = p.in[21] + (size_t)l * 512 + nb * 64;
; #pragma unroll
;     for (int n = 0; n < 4; ++n) {
;       f32x4 r = lds_mm<2>(xcs, LP, wid * 16, was, LP, n * 16, f32x4{0.f, 0.f, 0.f, 0.f});
;       f32x4 g = lds_mm<2>(xcs, LP, wid * 16, wxs, LP, n * 16, f32x4{0.f, 0.f, 0.f, 0.f});
;       const int j = n * 16 + fr;
;       const float sp = softplusf_(-lm[j]), bav = ba[j], bxv = bx[j];
.LBB0_1454:
	v_ashrrev_i32_e32 v0, 3, v2
	s_movk_i32 s10, 0x1ff
	v_cmp_lt_i32_e64 s[68:69], s10, v0
	s_movk_i32 s10, 0x200
	v_mov_b32_e32 v19, v184
	v_cmp_gt_i32_e32 vcc, s10, v0
	s_and_saveexec_b64 s[10:11], vcc
	s_xor_b64 s[10:11], exec, s[10:11]
	v_lshlrev_b32_e32 v1, 6, v0
	v_ashrrev_i32_e32 v8, 10, v2
	v_and_b32_e32 v13, 0x1fc0, v1
	s_or_saveexec_b64 s[38:39], s[10:11]
	v_mov_b32_e32 v40, 64
	s_xor_b64 exec, exec, s[38:39]
	v_add_u32_e32 v8, 0xfffffe00, v0
	v_mov_b32_e32 v1, 0x8000
	v_lshl_add_u32 v1, v8, 5, v1
	v_mov_b32_e32 v40, 32
	v_mov_b32_e32 v13, 0
	s_or_b64 exec, exec, s[38:39]
	v_and_b32_e32 v10, 7, v2
	v_mov_b32_e32 v43, v185
	v_lshlrev_b32_e32 v14, 6, v10
	v_and_b32_e32 v20, 63, v43
	v_or_b32_e32 v41, v20, v14
	v_lshlrev_b32_e32 v172, 2, v41
	v_lshl_add_u64 v[4:5], s[26:27], 0, v[172:173]
	v_add_co_u32_e32 v4, vcc, 0x1000, v4
	s_waitcnt vmcnt(0) lgkmcnt(0)
	s_barrier
	v_addc_co_u32_e32 v5, vcc, 0, v5, vcc
	global_load_dword v11, v172, s[26:27]
	global_load_dword v15, v172, s[26:27] offset:2048
	global_load_dword v16, v[4:5], off
	global_load_dword v17, v172, s[28:29]
	global_load_dword v18, v[4:5], off offset:2048
	v_lshlrev_b32_e32 v66, 13, v10
	v_mov_b32_e32 v67, v173
	v_lshlrev_b32_e32 v68, 4, v43
	v_and_b32_e32 v68, 0x70, v68
	v_mov_b32_e32 v69, v173
	v_lshl_add_u64 v[70:71], s[34:35], 0, v[66:67]
	v_lshl_add_u64 v[70:71], v[70:71], 0, v[68:69]
	v_lshl_add_u64 v[72:73], s[36:37], 0, v[66:67]
	v_lshl_add_u64 v[72:73], v[72:73], 0, v[68:69]
	v_ashrrev_i32_e32 v74, 3, v43
	v_lshlrev_b32_e32 v74, 6, v74
	v_ashrrev_i32_e32 v75, 31, v74
	v_lshlrev_b64 v[74:75], 1, v[74:75]
	v_lshl_add_u64 v[76:77], v[70:71], 0, v[74:75]
	global_load_dwordx4 v[100:103], v[76:77], off
	v_lshl_add_u64 v[76:77], v[72:73], 0, v[74:75]
	global_load_dwordx4 v[104:107], v[76:77], off
	v_add_u32_e32 v74, 0x100, v43
	v_ashrrev_i32_e32 v74, 3, v74
	v_lshlrev_b32_e32 v74, 6, v74
	v_ashrrev_i32_e32 v75, 31, v74
	v_lshlrev_b64 v[74:75], 1, v[74:75]
	v_lshl_add_u64 v[76:77], v[70:71], 0, v[74:75]
	global_load_dwordx4 v[108:111], v[76:77], off
	v_lshl_add_u64 v[76:77], v[72:73], 0, v[74:75]
	global_load_dwordx4 v[112:115], v[76:77], off
	v_and_b32_e32 v78, 15, v43
	v_lshl_or_b32 v78, v10, 6, v78
	v_lshlrev_b32_e32 v78, 2, v78
	global_load_dword v116, v78, s[6:7]
	global_load_dword v117, v78, s[6:7] offset:64
	global_load_dword v118, v78, s[6:7] offset:128
	global_load_dword v119, v78, s[6:7] offset:192
	global_load_dword v120, v78, s[12:13]
	global_load_dword v121, v78, s[12:13] offset:64
	global_load_dword v122, v78, s[12:13] offset:128
	global_load_dword v123, v78, s[12:13] offset:192
	global_load_dword v124, v78, s[4:5]
	global_load_dword v125, v78, s[4:5] offset:64
	global_load_dword v126, v78, s[4:5] offset:128
	global_load_dword v127, v78, s[4:5] offset:192
	v_mov_b64_e32 v[4:5], 0
	v_ashrrev_i32_e32 v9, 31, v8
	s_and_saveexec_b64 s[38:39], s[68:69]
	s_cbranch_execz .LBB0_1460
	v_readlane_b32 s40, v254, 41
	v_readlane_b32 s46, v254, 47
	v_readlane_b32 s47, v254, 48
	v_lshl_add_u64 v[4:5], s[30:31], 0, v[8:9]
	v_readlane_b32 s41, v254, 42
	v_mov_b64_e32 v[6:7], s[46:47]
	v_mad_u64_u32 v[6:7], s[10:11], v4, s97, v[6:7]
	v_mad_i32_i24 v7, v5, s97, v7
	v_lshl_add_u64 v[4:5], v[6:7], 0, v[172:173]
	v_readlane_b32 s42, v254, 43
	v_readlane_b32 s43, v254, 44
	v_readlane_b32 s44, v254, 45
	v_readlane_b32 s45, v254, 46
	v_readlane_b32 s48, v254, 49
	v_readlane_b32 s49, v254, 50
	v_readlane_b32 s50, v254, 51
	v_readlane_b32 s51, v254, 52
	v_readlane_b32 s52, v254, 53
	v_readlane_b32 s53, v254, 54
	v_readlane_b32 s54, v254, 55
	v_readlane_b32 s55, v254, 56

; DI float bf2f(u16 h) { return __uint_as_float(((unsigned)h) << 16); }
; DI float sigmoidf_(float x) { return __builtin_amdgcn_rcpf(1.f + __expf(-x)); }
; DI float softplusf_(float x) { return fmaxf(x, 0.f) + __logf(1.f + __expf(-fabsf(x))); }
; DI void lru1_item(const Params& p, int l, int it, char* smem) {
;     ...
; #pragma unroll
;     for (int n = 0; n < 4; ++n) {
;       f32x4 r = lds_mm<2>(xcs, LP, wid * 16, was, LP, n * 16, f32x4{0.f, 0.f, 0.f, 0.f});
;       f32x4 g = lds_mm<2>(xcs, LP, wid * 16, wxs, LP, n * 16, f32x4{0.f, 0.f, 0.f, 0.f});
;       const int j = n * 16 + fr;
;       const float sp = softplusf_(-lm[j]), bav = ba[j], bxv = bx[j];
; #pragma unroll
;       for (int q = 0; q < 4; ++q) {
;         const int t = wid * 16 + fq * 4 + q;
;         const float rr = sigmoidf_(r[q] + bav), ii = sigmoidf_(g[q] + bxv);
;         const float la = -8.f * rr * sp;
;         const float a = __expf(la);
;         const float x2 = 2.f * la;
;         const float om = (x2 > -0.01f) ? -x2 * (1.f + x2 * (0.5f + x2 * (1.f / 6.f))) : 1.f - __expf(x2);
;         const float u = sqrtf(om) * ii * bf2f(xcs[t * LP + j]);
;         as_[t * 64 + j] = a;
;         us_[t * 64 + j] = u;
;       }
;     }
.LBB0_1614:
	s_or_b64 exec, exec, s[72:73]
	v_mov_b32_e32 v4, v185
	s_waitcnt lgkmcnt(0)
	s_barrier
	v_lshlrev_b32_e32 v172, 2, v14
	v_and_b32_e32 v5, 15, v4
	v_or_b32_e32 v6, v5, v42
	v_mul_lo_u32 v6, v6, s70
	v_and_b32_e32 v4, 48, v4
	v_add3_u32 v13, v60, v6, v4
	v_mul_u32_u24_e32 v5, 0x90, v5
	v_add3_u32 v14, v60, v5, v4
	ds_read_b128 v[4:7], v13
	ds_read_b128 v[8:11], v14 offset:9216
	s_waitcnt lgkmcnt(0)
	v_mfma_f32_16x16x32_bf16 v[4:7], v[4:7], v[8:11], 0
	ds_read_b128 v[8:11], v13 offset:64
	ds_read_b128 v[14:17], v14 offset:9280
	v_and_b32_e32 v23, 15, v43
	v_lshl_add_u64 v[18:19], s[12:13], 0, v[172:173]
	s_waitcnt lgkmcnt(0)
	v_mfma_f32_16x16x32_bf16 v[8:11], v[8:11], v[14:17], v[4:7]
	v_lshl_add_u64 v[28:29], s[4:5], 0, v[172:173]
	s_nop 1
	v_mov_b32_e32 v4, v185
	v_lshl_add_u64 v[30:31], s[6:7], 0, v[172:173]
	v_and_b32_e32 v5, 15, v4
	v_or_b32_e32 v6, v5, v42
	v_mul_lo_u32 v6, v6, s70
	v_and_b32_e32 v4, 48, v4
	v_add3_u32 v13, v60, v6, v4
	v_mul_u32_u24_e32 v5, 0x90, v5
	v_add3_u32 v21, v60, v5, v4
	ds_read_b128 v[4:7], v13
	ds_read_b128 v[14:17], v21 offset:18432
	s_waitcnt lgkmcnt(0)
	v_mfma_f32_16x16x32_bf16 v[4:7], v[4:7], v[14:17], 0
	ds_read_b128 v[14:17], v13 offset:64
	ds_read_b128 v[24:27], v21 offset:18496
	v_lshlrev_b32_e32 v172, 2, v23
	s_waitcnt lgkmcnt(0)
	v_mfma_f32_16x16x32_bf16 v[4:7], v[14:17], v[24:27], v[4:7]
	v_lshl_add_u64 v[14:15], v[30:31], 0, v[172:173]
	s_waitcnt vmcnt(0)
	v_max_f32_e64 v16, -v116, -v116
	v_mul_f32_e64 v13, |v116|, s90
	v_exp_f32_e32 v13, v13
	v_max_f32_e32 v16, 0, v16
	v_add_f32_e32 v13, 1.0, v13
	v_cmp_gt_f32_e64 s[68:69], s1, v13
	s_nop 1
	v_cndmask_b32_e64 v17, 0, 32, s[68:69]
	v_ldexp_f32 v13, v13, v17
	v_log_f32_e32 v13, v13
	s_nop 0
	v_mul_f32_e32 v17, 0x3f317217, v13
	v_fma_f32 v17, v13, s91, -v17
	v_fmac_f32_e32 v17, 0x3377d1cf, v13
	v_fmac_f32_e32 v17, 0x3f317217, v13
	v_cmp_lt_f32_e64 s[72:73], |v13|, s84
	s_nop 1
	v_cndmask_b32_e64 v13, v13, v17, s[72:73]
	v_cndmask_b32_e64 v17, 0, v213, s[68:69]
	v_sub_f32_e32 v13, v13, v17
	v_add_f32_e32 v25, v16, v13
	v_lshl_add_u64 v[16:17], v[18:19], 0, v[172:173]
	v_lshl_add_u64 v[18:19], v[28:29], 0, v[172:173]
	s_waitcnt vmcnt(1)
	v_add_f32_e32 v8, v8, v120
	v_mul_f32_e32 v8, 0xbfb8aa3b, v8
	v_exp_f32_e32 v8, v8
	s_nop 0
	v_add_f32_e32 v8, 1.0, v8
	v_rcp_f32_e32 v8, v8
	s_nop 0
	v_mul_f32_e32 v8, 0xc1000000, v8
	v_mul_f32_e32 v8, v25, v8
	v_add_f32_e32 v21, v8, v8
	v_cmp_nlt_f32_e64 s[68:69], s85, v21
	s_and_saveexec_b64 s[10:11], s[68:69]
	s_xor_b64 s[10:11], exec, s[10:11]
	v_mul_f32_e32 v13, 0x3fb8aa3b, v21
	v_exp_f32_e32 v13, v13
	s_nop 0
	v_sub_f32_e32 v13, 1.0, v13
	s_andn2_saveexec_b64 s[10:11], s[10:11]
	s_mov_b32 s20, 0x3e2aaaab
	v_fma_f32 v13, v21, s20, 0.5
	v_fma_f32 v13, v21, v13, 1.0
	v_mul_f32_e64 v13, v13, -v21
	s_or_b64 exec, exec, s[10:11]
	s_waitcnt vmcnt(0)
	v_add_f32_e32 v4, v4, v124
	v_mul_f32_e32 v22, 0x4f800000, v13
	v_cmp_gt_f32_e64 s[68:69], s0, v13
	v_mul_f32_e32 v4, 0xbfb8aa3b, v4
	v_exp_f32_e32 v21, v4
	v_cndmask_b32_e64 v13, v13, v22, s[68:69]
	v_sqrt_f32_e32 v22, v13
	v_mul_f32_e32 v8, 0x3fb8aa3b, v8
	v_add_f32_e32 v21, 1.0, v21
	v_exp_f32_e32 v26, v8
	v_add_u32_e32 v8, -1, v22
	v_rcp_f32_e32 v24, v21
	v_fma_f32 v21, -v8, v22, v13
	v_cmp_ge_f32_e64 s[72:73], 0, v21
	v_add_u32_e32 v21, 1, v22
	v_lshrrev_b32_e32 v4, 2, v43
	v_cndmask_b32_e64 v8, v22, v8, s[72:73]
	v_fma_f32 v22, -v21, v22, v13
	v_cmp_lt_f32_e64 s[72:73], 0, v22
	v_add_f32_e32 v9, v9, v120
	v_and_or_b32 v4, v4, 12, v42
	v_cndmask_b32_e64 v8, v8, v21, s[72:73]
	v_mul_f32_e32 v21, 0x37800000, v8
	v_cndmask_b32_e64 v8, v8, v21, s[68:69]
	v_cmp_class_f32_e64 s[68:69], v13, v189
	v_mul_f32_e32 v9, 0xbfb8aa3b, v9
	v_mul_lo_u32 v21, v4, s70
	v_cndmask_b32_e64 v22, v8, v13, s[68:69]
	v_lshlrev_b32_e32 v8, 1, v23
	v_exp_f32_e32 v9, v9
	v_add3_u32 v13, v60, v21, v8
	ds_read_u16 v29, v13
	v_mul_f32_e32 v22, v24, v22
	v_add_f32_e32 v9, 1.0, v9
	v_rcp_f32_e32 v9, v9
	s_waitcnt lgkmcnt(0)
	v_lshlrev_b32_e32 v24, 16, v29
	v_mul_f32_e32 v22, v22, v24
	v_lshlrev_b32_e32 v24, 6, v4
	v_or_b32_e32 v29, v24, v23
	v_mul_f32_e32 v9, 0xc1000000, v9
	v_lshl_add_u32 v29, v29, 2, v60
	v_mul_f32_e32 v9, v25, v9
	ds_write2st64_b32 v29, v26, v22 offset0:108 offset1:172
	v_add_f32_e32 v26, v9, v9
	v_cmp_nlt_f32_e64 s[68:69], s85, v26
	s_and_saveexec_b64 s[10:11], s[68:69]
	s_xor_b64 s[10:11], exec, s[10:11]
	v_mul_f32_e32 v22, 0x3fb8aa3b, v26
	v_exp_f32_e32 v22, v22
	s_nop 0
	v_sub_f32_e32 v22, 1.0, v22
	s_andn2_saveexec_b64 s[10:11], s[10:11]
	s_mov_b32 s20, 0x3e2aaaab
	v_fma_f32 v22, v26, s20, 0.5
	v_fma_f32 v22, v26, v22, 1.0
	v_mul_f32_e64 v22, v22, -v26
	s_or_b64 exec, exec, s[10:11]
	v_add_f32_e32 v5, v5, v124
	v_mul_f32_e32 v5, 0xbfb8aa3b, v5
	v_exp_f32_e32 v5, v5
	v_mul_f32_e32 v26, 0x4f800000, v22
	v_cmp_gt_f32_e64 s[68:69], s0, v22
	v_add_f32_e32 v10, v10, v120
	v_add_f32_e32 v5, 1.0, v5
	v_cndmask_b32_e64 v22, v22, v26, s[68:69]
	v_sqrt_f32_e32 v26, v22
	v_rcp_f32_e32 v29, v5
	v_mul_f32_e32 v5, 0x3fb8aa3b, v9
	v_exp_f32_e32 v9, v5
	v_add_u32_e32 v5, -1, v26
	v_fma_f32 v30, -v5, v26, v22
	v_cmp_ge_f32_e64 s[72:73], 0, v30
	v_add_u32_e32 v30, 1, v26
	v_mul_f32_e32 v10, 0xbfb8aa3b, v10
	v_cndmask_b32_e64 v5, v26, v5, s[72:73]
	v_fma_f32 v26, -v30, v26, v22
	v_cmp_lt_f32_e64 s[72:73], 0, v26
	v_exp_f32_e32 v10, v10
	s_nop 0
	v_cndmask_b32_e64 v5, v5, v30, s[72:73]
	v_mul_f32_e32 v26, 0x37800000, v5
	v_cndmask_b32_e64 v5, v5, v26, s[68:69]
	v_cmp_class_f32_e64 s[68:69], v22, v189
	v_add_f32_e32 v10, 1.0, v10
	v_rcp_f32_e32 v10, v10
	v_cndmask_b32_e64 v22, v5, v22, s[68:69]
	v_add_u32_e32 v5, 0x90, v21
	v_add3_u32 v21, v60, v5, v8
	ds_read_u16 v26, v21
	v_mul_f32_e32 v22, v29, v22
	s_waitcnt lgkmcnt(0)
; DI float bf2f(u16 h) { return __uint_as_float(((unsigned)h) << 16); }
; DI float sigmoidf_(float x) { return __builtin_amdgcn_rcpf(1.f + __expf(-x)); }
; DI float softplusf_(float x) { return fmaxf(x, 0.f) + __logf(1.f + __expf(-fabsf(x))); }
; DI void lru1_item(const Params& p, int l, int it, char* smem) {
;     ...
; #pragma unroll
;     for (int n = 0; n < 4; ++n) {
;       f32x4 r = lds_mm<2>(xcs, LP, wid * 16, was, LP, n * 16, f32x4{0.f, 0.f, 0.f, 0.f});
;       f32x4 g = lds_mm<2>(xcs, LP, wid * 16, wxs, LP, n * 16, f32x4{0.f, 0.f, 0.f, 0.f});
;       const int j = n * 16 + fr;
;       const float sp = softplusf_(-lm[j]), bav = ba[j], bxv = bx[j];
; #pragma unroll
;       for (int q = 0; q < 4; ++q) {
;         const int t = wid * 16 + fq * 4 + q;
;         const float rr = sigmoidf_(r[q] + bav), ii = sigmoidf_(g[q] + bxv);
;         const float la = -8.f * rr * sp;
;         const float a = __expf(la);
;         const float x2 = 2.f * la;
;         const float om = (x2 > -0.01f) ? -x2 * (1.f + x2 * (0.5f + x2 * (1.f / 6.f))) : 1.f - __expf(x2);
;         const float u = sqrtf(om) * ii * bf2f(xcs[t * LP + j]);
;         as_[t * 64 + j] = a;
;         us_[t * 64 + j] = u;
;       }
;     }
	v_lshlrev_b32_e32 v26, 16, v26
	v_mul_f32_e32 v22, v22, v26
	v_lshl_or_b32 v26, v4, 6, 64
	v_or_b32_e32 v29, v26, v23
	v_lshl_add_u32 v29, v29, 2, v60
	ds_write2st64_b32 v29, v9, v22 offset0:108 offset1:172
	v_mul_f32_e32 v9, 0xc1000000, v10
	v_mul_f32_e32 v9, v25, v9
	v_add_f32_e32 v22, v9, v9
	v_cmp_nlt_f32_e64 s[68:69], s85, v22
	s_and_saveexec_b64 s[10:11], s[68:69]
	s_xor_b64 s[10:11], exec, s[10:11]
	v_mul_f32_e32 v10, 0x3fb8aa3b, v22
	v_exp_f32_e32 v10, v10
	s_nop 0
	v_sub_f32_e32 v10, 1.0, v10
	s_andn2_saveexec_b64 s[10:11], s[10:11]
	s_mov_b32 s20, 0x3e2aaaab
	v_fma_f32 v10, v22, s20, 0.5
	v_fma_f32 v10, v22, v10, 1.0
	v_mul_f32_e64 v10, v10, -v22
	s_or_b64 exec, exec, s[10:11]
	v_mul_f32_e32 v22, 0x4f800000, v10
	v_cmp_gt_f32_e64 s[68:69], s0, v10
	v_add_f32_e32 v6, v6, v124
	v_mul_f32_e32 v6, 0xbfb8aa3b, v6
	v_cndmask_b32_e64 v10, v10, v22, s[68:69]
	v_sqrt_f32_e32 v22, v10
	v_exp_f32_e32 v6, v6
	v_add_u32_e32 v5, 0x90, v5
	v_mul_f32_e32 v9, 0x3fb8aa3b, v9
	v_add_u32_e32 v29, -1, v22
	v_fma_f32 v30, -v29, v22, v10
	v_cmp_ge_f32_e64 s[72:73], 0, v30
	v_add_u32_e32 v30, 1, v22
	v_add_f32_e32 v6, 1.0, v6
	v_cndmask_b32_e64 v29, v22, v29, s[72:73]
	v_fma_f32 v22, -v30, v22, v10
	v_cmp_lt_f32_e64 s[72:73], 0, v22
	v_rcp_f32_e32 v6, v6
	v_exp_f32_e32 v9, v9
	v_cndmask_b32_e64 v22, v29, v30, s[72:73]
	v_mul_f32_e32 v29, 0x37800000, v22
	v_cndmask_b32_e64 v22, v22, v29, s[68:69]
	v_cmp_class_f32_e64 s[68:69], v10, v189
	s_nop 1
	v_cndmask_b32_e64 v10, v22, v10, s[68:69]
	v_add3_u32 v22, v60, v5, v8
	ds_read_u16 v5, v22
	v_add_f32_e32 v8, v11, v120
	v_mul_f32_e32 v8, 0xbfb8aa3b, v8
	v_exp_f32_e32 v8, v8
	v_mul_f32_e32 v6, v6, v10
	s_waitcnt lgkmcnt(0)
	v_lshlrev_b32_e32 v5, 16, v5
	v_mul_f32_e32 v5, v6, v5
	v_add_f32_e32 v6, 1.0, v8
	v_rcp_f32_e32 v6, v6
	v_lshl_or_b32 v27, v4, 6, v196
	v_or_b32_e32 v8, v27, v23
	v_lshl_add_u32 v8, v8, 2, v60
	ds_write2st64_b32 v8, v9, v5 offset0:108 offset1:172
	v_mul_f32_e32 v5, 0xc1000000, v6
	v_mul_f32_e32 v6, v25, v5
	v_add_f32_e32 v8, v6, v6
	v_cmp_nlt_f32_e64 s[68:69], s85, v8
	s_and_saveexec_b64 s[10:11], s[68:69]
	s_xor_b64 s[10:11], exec, s[10:11]
	v_mul_f32_e32 v5, 0x3fb8aa3b, v8
	v_exp_f32_e32 v5, v5
	s_nop 0
	v_sub_f32_e32 v5, 1.0, v5
	s_andn2_saveexec_b64 s[10:11], s[10:11]
	s_mov_b32 s20, 0x3e2aaaab
	v_fma_f32 v5, v8, s20, 0.5
	v_fma_f32 v5, v8, v5, 1.0
	v_mul_f32_e64 v5, v5, -v8
	s_or_b64 exec, exec, s[10:11]
	v_cmp_gt_f32_e64 s[68:69], s0, v5
	v_mul_f32_e32 v8, 0x4f800000, v5
	v_add_f32_e32 v7, v7, v124
	v_cndmask_b32_e64 v5, v5, v8, s[68:69]
	v_sqrt_f32_e32 v8, v5
	v_mul_f32_e32 v7, 0xbfb8aa3b, v7
	v_exp_f32_e32 v7, v7
	v_mul_f32_e32 v6, 0x3fb8aa3b, v6
	v_add_u32_e32 v9, -1, v8
	v_fma_f32 v10, -v9, v8, v5
	v_cmp_ge_f32_e64 s[72:73], 0, v10
	v_add_u32_e32 v10, 1, v8
	v_add_f32_e32 v7, 1.0, v7
	v_cndmask_b32_e64 v9, v8, v9, s[72:73]
	v_fma_f32 v8, -v10, v8, v5
	v_cmp_lt_f32_e64 s[72:73], 0, v8
	v_rcp_f32_e32 v7, v7
	v_exp_f32_e32 v6, v6
	v_cndmask_b32_e64 v8, v9, v10, s[72:73]
	v_mul_f32_e32 v9, 0x37800000, v8
	v_cndmask_b32_e64 v8, v8, v9, s[68:69]
	v_cmp_class_f32_e64 s[68:69], v5, v189
	v_lshl_or_b32 v28, v4, 6, v197
	v_or_b32_e32 v4, v28, v23
	v_cndmask_b32_e64 v5, v8, v5, s[68:69]
	v_mul_f32_e32 v5, v7, v5
	ds_read_u16 v7, v22 offset:144
	v_lshl_add_u32 v4, v4, 2, v60
	s_waitcnt lgkmcnt(0)
	v_lshlrev_b32_e32 v7, 16, v7
	v_mul_f32_e32 v5, v5, v7
	ds_write2st64_b32 v4, v6, v5 offset0:108 offset1:172
	v_mov_b32_e32 v4, v185
	s_nop 0
	v_and_b32_e32 v5, 15, v4
	v_or_b32_e32 v6, v5, v42
	v_mul_lo_u32 v6, v6, s70
	v_and_b32_e32 v4, 48, v4
	v_add3_u32 v25, v60, v6, v4
	v_mul_u32_u24_e32 v5, 0x90, v5
	v_add3_u32 v29, v60, v5, v4
	ds_read_b128 v[4:7], v25
	ds_read_b128 v[8:11], v29 offset:11520
	s_waitcnt lgkmcnt(0)
	v_mfma_f32_16x16x32_bf16 v[4:7], v[4:7], v[8:11], 0
	ds_read_b128 v[8:11], v25 offset:64
	ds_read_b128 v[30:33], v29 offset:11584
	s_waitcnt lgkmcnt(0)
	v_mfma_f32_16x16x32_bf16 v[8:11], v[8:11], v[30:33], v[4:7]
	s_nop 3
	v_mov_b32_e32 v4, v185
	s_nop 0
	v_and_b32_e32 v5, 15, v4
	v_or_b32_e32 v6, v5, v42
	v_mul_lo_u32 v6, v6, s70
	v_and_b32_e32 v4, 48, v4
	v_add3_u32 v25, v60, v6, v4
	v_mul_u32_u24_e32 v5, 0x90, v5
	v_add3_u32 v29, v60, v5, v4
	ds_read_b128 v[4:7], v25
	ds_read_b128 v[30:33], v29 offset:20736
	s_waitcnt lgkmcnt(0)
	v_mfma_f32_16x16x32_bf16 v[4:7], v[4:7], v[30:33], 0
	ds_read_b128 v[30:33], v25 offset:64
	ds_read_b128 v[34:37], v29 offset:20800
	s_waitcnt vmcnt(0)
	v_max_f32_e64 v29, -v117, -v117
	v_mul_f32_e64 v25, |v117|, s90
	v_exp_f32_e32 v25, v25
	s_waitcnt lgkmcnt(0)
	v_mfma_f32_16x16x32_bf16 v[4:7], v[30:33], v[34:37], v[4:7]
	v_max_f32_e32 v29, 0, v29
	v_add_f32_e32 v25, 1.0, v25
	v_cmp_gt_f32_e64 s[68:69], s1, v25
	s_nop 1
	v_cndmask_b32_e64 v30, 0, 32, s[68:69]
	v_ldexp_f32 v25, v25, v30
	v_log_f32_e32 v25, v25
	s_nop 0
	v_mul_f32_e32 v30, 0x3f317217, v25
	v_fma_f32 v30, v25, s91, -v30
	v_fmac_f32_e32 v30, 0x3377d1cf, v25
	v_fmac_f32_e32 v30, 0x3f317217, v25
	v_cmp_lt_f32_e64 s[72:73], |v25|, s84
	s_nop 1
	v_cndmask_b32_e64 v25, v25, v30, s[72:73]
	v_cndmask_b32_e64 v30, 0, v213, s[68:69]
	v_sub_f32_e32 v25, v25, v30
	v_add_f32_e32 v29, v29, v25
	s_waitcnt vmcnt(1)
	v_add_f32_e32 v8, v8, v121
	v_mul_f32_e32 v8, 0xbfb8aa3b, v8
	v_exp_f32_e32 v8, v8
	s_nop 0
	v_add_f32_e32 v8, 1.0, v8
	v_rcp_f32_e32 v8, v8
	s_nop 0
	v_mul_f32_e32 v8, 0xc1000000, v8
	v_mul_f32_e32 v8, v29, v8
	v_add_f32_e32 v32, v8, v8
	v_cmp_nlt_f32_e64 s[68:69], s85, v32
	s_and_saveexec_b64 s[10:11], s[68:69]
	s_xor_b64 s[10:11], exec, s[10:11]
	v_mul_f32_e32 v25, 0x3fb8aa3b, v32
	v_exp_f32_e32 v25, v25
	s_nop 0
	v_sub_f32_e32 v25, 1.0, v25
	s_andn2_saveexec_b64 s[10:11], s[10:11]
	s_mov_b32 s20, 0x3e2aaaab
	v_fma_f32 v25, v32, s20, 0.5
	v_fma_f32 v25, v32, v25, 1.0
	v_mul_f32_e64 v25, v25, -v32
	s_or_b64 exec, exec, s[10:11]
	v_mul_f32_e32 v32, 0x4f800000, v25
	v_cmp_gt_f32_e64 s[68:69], s0, v25
	s_waitcnt vmcnt(0)
; DI float bf2f(u16 h) { return __uint_as_float(((unsigned)h) << 16); }
; DI float sigmoidf_(float x) { return __builtin_amdgcn_rcpf(1.f + __expf(-x)); }
; DI float softplusf_(float x) { return fmaxf(x, 0.f) + __logf(1.f + __expf(-fabsf(x))); }
; DI void lru1_item(const Params& p, int l, int it, char* smem) {
;     ...
; #pragma unroll
;     for (int n = 0; n < 4; ++n) {
;       f32x4 r = lds_mm<2>(xcs, LP, wid * 16, was, LP, n * 16, f32x4{0.f, 0.f, 0.f, 0.f});
;       f32x4 g = lds_mm<2>(xcs, LP, wid * 16, wxs, LP, n * 16, f32x4{0.f, 0.f, 0.f, 0.f});
;       const int j = n * 16 + fr;
;       const float sp = softplusf_(-lm[j]), bav = ba[j], bxv = bx[j];
; #pragma unroll
;       for (int q = 0; q < 4; ++q) {
;         const int t = wid * 16 + fq * 4 + q;
;         const float rr = sigmoidf_(r[q] + bav), ii = sigmoidf_(g[q] + bxv);
;         const float la = -8.f * rr * sp;
;         const float a = __expf(la);
;         const float x2 = 2.f * la;
;         const float om = (x2 > -0.01f) ? -x2 * (1.f + x2 * (0.5f + x2 * (1.f / 6.f))) : 1.f - __expf(x2);
;         const float u = sqrtf(om) * ii * bf2f(xcs[t * LP + j]);
;         as_[t * 64 + j] = a;
;         us_[t * 64 + j] = u;
;       }
;     }
	v_add_f32_e32 v4, v4, v125
	v_mul_f32_e32 v4, 0xbfb8aa3b, v4
	v_cndmask_b32_e64 v25, v25, v32, s[68:69]
	v_sqrt_f32_e32 v32, v25
	v_exp_f32_e32 v4, v4
	v_add_f32_e32 v9, v9, v121
	v_mul_f32_e32 v9, 0xbfb8aa3b, v9
	v_add_u32_e32 v33, -1, v32
	v_fma_f32 v34, -v33, v32, v25
	v_cmp_ge_f32_e64 s[72:73], 0, v34
	v_add_u32_e32 v34, 1, v32
	v_exp_f32_e32 v9, v9
	v_cndmask_b32_e64 v33, v32, v33, s[72:73]
	v_fma_f32 v32, -v34, v32, v25
	v_cmp_lt_f32_e64 s[72:73], 0, v32
	v_add_f32_e32 v4, 1.0, v4
	v_rcp_f32_e32 v4, v4
	v_cndmask_b32_e64 v32, v33, v34, s[72:73]
	v_mul_f32_e32 v33, 0x37800000, v32
	v_cndmask_b32_e64 v32, v32, v33, s[68:69]
	v_cmp_class_f32_e64 s[68:69], v25, v189
	v_mul_f32_e32 v8, 0x3fb8aa3b, v8
	v_add_f32_e32 v9, 1.0, v9
	v_cndmask_b32_e64 v25, v32, v25, s[68:69]
	ds_read_u16 v32, v13 offset:32
	v_exp_f32_e32 v8, v8
	v_rcp_f32_e32 v9, v9
	v_mul_f32_e32 v4, v4, v25
	v_add_u32_e32 v24, v24, v23
	s_waitcnt lgkmcnt(0)
	v_lshlrev_b32_e32 v25, 16, v32
	v_mul_f32_e32 v4, v4, v25
	v_lshl_add_u32 v25, v24, 2, v60
	v_add_u32_e32 v24, 64, v25
	ds_write2st64_b32 v24, v8, v4 offset0:108 offset1:172
	v_mul_f32_e32 v4, 0xc1000000, v9
	v_mul_f32_e32 v4, v29, v4
	v_add_f32_e32 v9, v4, v4
	v_cmp_nlt_f32_e64 s[68:69], s85, v9
	s_and_saveexec_b64 s[10:11], s[68:69]
	s_xor_b64 s[10:11], exec, s[10:11]
	v_mul_f32_e32 v8, 0x3fb8aa3b, v9
	v_exp_f32_e32 v8, v8
	s_nop 0
	v_sub_f32_e32 v8, 1.0, v8
	s_andn2_saveexec_b64 s[10:11], s[10:11]
	s_mov_b32 s20, 0x3e2aaaab
	v_fma_f32 v8, v9, s20, 0.5
	v_fma_f32 v8, v9, v8, 1.0
	v_mul_f32_e64 v8, v8, -v9
	s_or_b64 exec, exec, s[10:11]
	v_mul_f32_e32 v9, 0x4f800000, v8
	v_cmp_gt_f32_e64 s[68:69], s0, v8
	v_add_f32_e32 v5, v5, v125
	v_mul_f32_e32 v5, 0xbfb8aa3b, v5
	v_cndmask_b32_e64 v8, v8, v9, s[68:69]
	v_sqrt_f32_e32 v9, v8
	v_exp_f32_e32 v5, v5
	v_mul_f32_e32 v4, 0x3fb8aa3b, v4
	v_exp_f32_e32 v4, v4
	v_add_u32_e32 v24, -1, v9
	v_fma_f32 v32, -v24, v9, v8
	v_cmp_ge_f32_e64 s[72:73], 0, v32
	v_add_u32_e32 v32, 1, v9
	v_add_f32_e32 v5, 1.0, v5
	v_cndmask_b32_e64 v24, v9, v24, s[72:73]
	v_fma_f32 v9, -v32, v9, v8
	v_cmp_lt_f32_e64 s[72:73], 0, v9
	v_rcp_f32_e32 v5, v5
	s_nop 0
	v_cndmask_b32_e64 v9, v24, v32, s[72:73]
	v_mul_f32_e32 v24, 0x37800000, v9
	v_cndmask_b32_e64 v9, v9, v24, s[68:69]
	v_cmp_class_f32_e64 s[68:69], v8, v189
	s_nop 1
	v_cndmask_b32_e64 v8, v9, v8, s[68:69]
	v_mul_f32_e32 v5, v5, v8
	v_add_f32_e32 v8, v10, v121
	v_mul_f32_e32 v8, 0xbfb8aa3b, v8
	ds_read_u16 v9, v21 offset:32
	v_exp_f32_e32 v8, v8
	s_waitcnt lgkmcnt(0)
	v_lshlrev_b32_e32 v9, 16, v9
	v_add_f32_e32 v8, 1.0, v8
	v_rcp_f32_e32 v8, v8
	v_mul_f32_e32 v5, v5, v9
	v_add_u32_e32 v9, v26, v23
	v_lshl_add_u32 v26, v9, 2, v60
	v_add_u32_e32 v9, 64, v26
	ds_write2st64_b32 v9, v4, v5 offset0:108 offset1:172
	v_mul_f32_e32 v4, 0xc1000000, v8
	v_mul_f32_e32 v4, v29, v4
	v_add_f32_e32 v8, v4, v4
	v_cmp_nlt_f32_e64 s[68:69], s85, v8
	s_and_saveexec_b64 s[10:11], s[68:69]
	s_xor_b64 s[10:11], exec, s[10:11]
	v_mul_f32_e32 v5, 0x3fb8aa3b, v8
	v_exp_f32_e32 v5, v5
	s_nop 0
	v_sub_f32_e32 v5, 1.0, v5
	s_andn2_saveexec_b64 s[10:11], s[10:11]
	s_mov_b32 s20, 0x3e2aaaab
	v_fma_f32 v5, v8, s20, 0.5
	v_fma_f32 v5, v8, v5, 1.0
	v_mul_f32_e64 v5, v5, -v8
	s_or_b64 exec, exec, s[10:11]
	v_mul_f32_e32 v8, 0x4f800000, v5
	v_cmp_gt_f32_e64 s[68:69], s0, v5
	v_add_f32_e32 v6, v6, v125
	v_mul_f32_e32 v6, 0xbfb8aa3b, v6
	v_cndmask_b32_e64 v5, v5, v8, s[68:69]
	v_sqrt_f32_e32 v8, v5
	v_exp_f32_e32 v6, v6
	v_mul_f32_e32 v4, 0x3fb8aa3b, v4
	v_exp_f32_e32 v4, v4
	v_add_u32_e32 v9, -1, v8
	v_fma_f32 v10, -v9, v8, v5
	v_cmp_ge_f32_e64 s[72:73], 0, v10
	v_add_u32_e32 v10, 1, v8
	v_add_f32_e32 v6, 1.0, v6
	v_cndmask_b32_e64 v9, v8, v9, s[72:73]
	v_fma_f32 v8, -v10, v8, v5
	v_cmp_lt_f32_e64 s[72:73], 0, v8
	v_rcp_f32_e32 v6, v6
	s_nop 0
	v_cndmask_b32_e64 v8, v9, v10, s[72:73]
	v_mul_f32_e32 v9, 0x37800000, v8
	v_cndmask_b32_e64 v8, v8, v9, s[68:69]
	v_cmp_class_f32_e64 s[68:69], v5, v189
	s_nop 1
	v_cndmask_b32_e64 v5, v8, v5, s[68:69]
	v_mul_f32_e32 v5, v6, v5
	v_add_f32_e32 v6, v11, v121
	v_mul_f32_e32 v6, 0xbfb8aa3b, v6
	ds_read_u16 v8, v22 offset:32
	v_exp_f32_e32 v6, v6
	s_waitcnt lgkmcnt(0)
	v_lshlrev_b32_e32 v8, 16, v8
	v_add_f32_e32 v6, 1.0, v6
	v_rcp_f32_e32 v6, v6
	v_mul_f32_e32 v5, v5, v8
	v_add_u32_e32 v8, v27, v23
	v_lshl_add_u32 v27, v8, 2, v60
	v_add_u32_e32 v8, 64, v27
	ds_write2st64_b32 v8, v4, v5 offset0:108 offset1:172
	v_mul_f32_e32 v4, 0xc1000000, v6
	v_mul_f32_e32 v5, v29, v4
	v_add_f32_e32 v6, v5, v5
	v_cmp_nlt_f32_e64 s[68:69], s85, v6
	s_and_saveexec_b64 s[10:11], s[68:69]
	s_xor_b64 s[10:11], exec, s[10:11]
	v_mul_f32_e32 v4, 0x3fb8aa3b, v6
	v_exp_f32_e32 v4, v4
	s_nop 0
	v_sub_f32_e32 v4, 1.0, v4
	s_andn2_saveexec_b64 s[10:11], s[10:11]
	s_mov_b32 s20, 0x3e2aaaab
	v_fma_f32 v4, v6, s20, 0.5
	v_fma_f32 v4, v6, v4, 1.0
	v_mul_f32_e64 v4, v4, -v6
	s_or_b64 exec, exec, s[10:11]
	v_add_f32_e32 v6, v7, v125
	v_cmp_gt_f32_e64 s[68:69], s0, v4
	v_mul_f32_e32 v7, 0x4f800000, v4
	v_mul_f32_e32 v6, 0xbfb8aa3b, v6
	v_cndmask_b32_e64 v4, v4, v7, s[68:69]
	v_sqrt_f32_e32 v7, v4
	v_exp_f32_e32 v6, v6
	v_add_u32_e32 v24, 0x90, v22
	v_mul_f32_e32 v5, 0x3fb8aa3b, v5
	v_add_u32_e32 v8, -1, v7
	v_fma_f32 v9, -v8, v7, v4
	v_cmp_ge_f32_e64 s[72:73], 0, v9
	v_add_u32_e32 v9, 1, v7
	v_add_f32_e32 v6, 1.0, v6
	v_cndmask_b32_e64 v8, v7, v8, s[72:73]
	v_fma_f32 v7, -v9, v7, v4
	v_cmp_lt_f32_e64 s[72:73], 0, v7
	v_rcp_f32_e32 v6, v6
	v_exp_f32_e32 v5, v5
	v_cndmask_b32_e64 v7, v8, v9, s[72:73]
	v_mul_f32_e32 v8, 0x37800000, v7
	v_cndmask_b32_e64 v7, v7, v8, s[68:69]
	v_cmp_class_f32_e64 s[68:69], v4, v189
	s_nop 1
	v_cndmask_b32_e64 v4, v7, v4, s[68:69]
	v_mul_f32_e32 v4, v6, v4
	ds_read_u16 v6, v24 offset:32
	s_waitcnt lgkmcnt(0)
; DI float bf2f(u16 h) { return __uint_as_float(((unsigned)h) << 16); }
; DI float sigmoidf_(float x) { return __builtin_amdgcn_rcpf(1.f + __expf(-x)); }
; DI float softplusf_(float x) { return fmaxf(x, 0.f) + __logf(1.f + __expf(-fabsf(x))); }
; DI void lru1_item(const Params& p, int l, int it, char* smem) {
;     ...
; #pragma unroll
;     for (int n = 0; n < 4; ++n) {
;       f32x4 r = lds_mm<2>(xcs, LP, wid * 16, was, LP, n * 16, f32x4{0.f, 0.f, 0.f, 0.f});
;       f32x4 g = lds_mm<2>(xcs, LP, wid * 16, wxs, LP, n * 16, f32x4{0.f, 0.f, 0.f, 0.f});
;       const int j = n * 16 + fr;
;       const float sp = softplusf_(-lm[j]), bav = ba[j], bxv = bx[j];
; #pragma unroll
;       for (int q = 0; q < 4; ++q) {
;         const int t = wid * 16 + fq * 4 + q;
;         const float rr = sigmoidf_(r[q] + bav), ii = sigmoidf_(g[q] + bxv);
;         const float la = -8.f * rr * sp;
;         const float a = __expf(la);
;         const float x2 = 2.f * la;
;         const float om = (x2 > -0.01f) ? -x2 * (1.f + x2 * (0.5f + x2 * (1.f / 6.f))) : 1.f - __expf(x2);
;         const float u = sqrtf(om) * ii * bf2f(xcs[t * LP + j]);
;         as_[t * 64 + j] = a;
;         us_[t * 64 + j] = u;
;       }
;     }
	v_lshlrev_b32_e32 v6, 16, v6
	v_mul_f32_e32 v4, v4, v6
	v_add_u32_e32 v6, v28, v23
	v_lshl_add_u32 v23, v6, 2, v60
	v_add_u32_e32 v6, 64, v23
	ds_write2st64_b32 v6, v5, v4 offset0:108 offset1:172
	v_mov_b32_e32 v4, v185
	s_nop 0
	v_and_b32_e32 v5, 15, v4
	v_or_b32_e32 v6, v5, v42
	v_mul_lo_u32 v6, v6, s70
	v_and_b32_e32 v4, 48, v4
	v_add3_u32 v28, v60, v6, v4
	v_mul_u32_u24_e32 v5, 0x90, v5
	v_add3_u32 v29, v60, v5, v4
	ds_read_b128 v[4:7], v28
	ds_read_b128 v[8:11], v29 offset:13824
	s_waitcnt lgkmcnt(0)
	v_mfma_f32_16x16x32_bf16 v[4:7], v[4:7], v[8:11], 0
	ds_read_b128 v[8:11], v28 offset:64
	ds_read_b128 v[28:31], v29 offset:13888
	s_waitcnt lgkmcnt(0)
	v_mfma_f32_16x16x32_bf16 v[8:11], v[8:11], v[28:31], v[4:7]
	s_nop 3
	v_mov_b32_e32 v4, v185
	s_nop 0
	v_and_b32_e32 v5, 15, v4
	v_or_b32_e32 v6, v5, v42
	v_mul_lo_u32 v6, v6, s70
	v_and_b32_e32 v4, 48, v4
	v_add3_u32 v32, v60, v6, v4
	v_mul_u32_u24_e32 v5, 0x90, v5
	v_add3_u32 v33, v60, v5, v4
	ds_read_b128 v[4:7], v32
	ds_read_b128 v[28:31], v33 offset:23040
	s_waitcnt lgkmcnt(0)
	v_mfma_f32_16x16x32_bf16 v[4:7], v[4:7], v[28:31], 0
	ds_read_b128 v[28:31], v32 offset:64
	ds_read_b128 v[32:35], v33 offset:23104
	s_waitcnt lgkmcnt(0)
	v_mfma_f32_16x16x32_bf16 v[4:7], v[28:31], v[32:35], v[4:7]
	s_waitcnt vmcnt(0)
	v_max_f32_e64 v29, -v118, -v118
	v_mul_f32_e64 v28, |v118|, s90
	v_exp_f32_e32 v28, v28
	v_max_f32_e32 v29, 0, v29
	v_add_f32_e32 v28, 1.0, v28
	v_cmp_gt_f32_e64 s[68:69], s1, v28
	s_nop 1
	v_cndmask_b32_e64 v30, 0, 32, s[68:69]
	v_ldexp_f32 v28, v28, v30
	v_log_f32_e32 v28, v28
	s_nop 0
	v_mul_f32_e32 v30, 0x3f317217, v28
	v_fma_f32 v30, v28, s91, -v30
	v_fmac_f32_e32 v30, 0x3377d1cf, v28
	v_fmac_f32_e32 v30, 0x3f317217, v28
	v_cmp_lt_f32_e64 s[72:73], |v28|, s84
	s_nop 1
	v_cndmask_b32_e64 v28, v28, v30, s[72:73]
	v_cndmask_b32_e64 v30, 0, v213, s[68:69]
	v_sub_f32_e32 v28, v28, v30
	v_add_f32_e32 v28, v29, v28
	s_waitcnt vmcnt(1)
	v_add_f32_e32 v8, v8, v122
	v_mul_f32_e32 v8, 0xbfb8aa3b, v8
	v_exp_f32_e32 v8, v8
	s_nop 0
	v_add_f32_e32 v8, 1.0, v8
	v_rcp_f32_e32 v8, v8
	s_nop 0
	v_mul_f32_e32 v8, 0xc1000000, v8
	v_mul_f32_e32 v8, v28, v8
	v_add_f32_e32 v32, v8, v8
	v_cmp_nlt_f32_e64 s[68:69], s85, v32
	s_and_saveexec_b64 s[10:11], s[68:69]
	s_xor_b64 s[10:11], exec, s[10:11]
	v_mul_f32_e32 v31, 0x3fb8aa3b, v32
	v_exp_f32_e32 v31, v31
	s_nop 0
	v_sub_f32_e32 v31, 1.0, v31
	s_andn2_saveexec_b64 s[10:11], s[10:11]
	s_mov_b32 s20, 0x3e2aaaab
	v_fma_f32 v31, v32, s20, 0.5
	v_fma_f32 v31, v32, v31, 1.0
	v_mul_f32_e64 v31, v31, -v32
	s_or_b64 exec, exec, s[10:11]
	v_mul_f32_e32 v32, 0x4f800000, v31
	v_cmp_gt_f32_e64 s[68:69], s0, v31
	s_waitcnt vmcnt(0)
	v_add_f32_e32 v4, v4, v126
	v_mul_f32_e32 v4, 0xbfb8aa3b, v4
	v_cndmask_b32_e64 v31, v31, v32, s[68:69]
	v_sqrt_f32_e32 v32, v31
	v_exp_f32_e32 v4, v4
	v_add_f32_e32 v9, v9, v122
	v_mul_f32_e32 v9, 0xbfb8aa3b, v9
	v_add_u32_e32 v33, -1, v32
	v_fma_f32 v34, -v33, v32, v31
	v_cmp_ge_f32_e64 s[72:73], 0, v34
	v_add_u32_e32 v34, 1, v32
	v_exp_f32_e32 v9, v9
	v_cndmask_b32_e64 v33, v32, v33, s[72:73]
	v_fma_f32 v32, -v34, v32, v31
	v_cmp_lt_f32_e64 s[72:73], 0, v32
	v_add_f32_e32 v4, 1.0, v4
	v_rcp_f32_e32 v4, v4
	v_cndmask_b32_e64 v32, v33, v34, s[72:73]
	v_mul_f32_e32 v33, 0x37800000, v32
	v_cndmask_b32_e64 v32, v32, v33, s[68:69]
	ds_read_u16 v33, v13 offset:64
	v_mul_f32_e32 v8, 0x3fb8aa3b, v8
	v_add_f32_e32 v9, 1.0, v9
	v_exp_f32_e32 v8, v8
	v_cmp_class_f32_e64 s[68:69], v31, v189
	v_rcp_f32_e32 v9, v9
	s_nop 0
	v_cndmask_b32_e64 v31, v32, v31, s[68:69]
	v_mul_f32_e32 v4, v4, v31
	s_waitcnt lgkmcnt(0)
	v_lshlrev_b32_e32 v31, 16, v33
	v_mul_f32_e32 v4, v4, v31
	v_add_u32_e32 v31, 0x80, v25
	ds_write2st64_b32 v31, v8, v4 offset0:108 offset1:172
	v_mul_f32_e32 v4, 0xc1000000, v9
	v_mul_f32_e32 v4, v28, v4
	v_add_f32_e32 v9, v4, v4
	v_cmp_nlt_f32_e64 s[68:69], s85, v9
	s_and_saveexec_b64 s[10:11], s[68:69]
	s_xor_b64 s[10:11], exec, s[10:11]
	v_mul_f32_e32 v8, 0x3fb8aa3b, v9
	v_exp_f32_e32 v8, v8
	s_nop 0
	v_sub_f32_e32 v8, 1.0, v8
	s_andn2_saveexec_b64 s[10:11], s[10:11]
	s_mov_b32 s20, 0x3e2aaaab
	v_fma_f32 v8, v9, s20, 0.5
	v_fma_f32 v8, v9, v8, 1.0
	v_mul_f32_e64 v8, v8, -v9
	s_or_b64 exec, exec, s[10:11]
	v_mul_f32_e32 v9, 0x4f800000, v8
	v_cmp_gt_f32_e64 s[68:69], s0, v8
	v_add_f32_e32 v5, v5, v126
	v_mul_f32_e32 v5, 0xbfb8aa3b, v5
	v_cndmask_b32_e64 v8, v8, v9, s[68:69]
	v_sqrt_f32_e32 v9, v8
	v_exp_f32_e32 v5, v5
	v_add_f32_e32 v10, v10, v122
	v_mul_f32_e32 v10, 0xbfb8aa3b, v10
	v_add_u32_e32 v31, -1, v9
	v_fma_f32 v32, -v31, v9, v8
	v_cmp_ge_f32_e64 s[72:73], 0, v32
	v_add_u32_e32 v32, 1, v9
	v_exp_f32_e32 v10, v10
	v_cndmask_b32_e64 v31, v9, v31, s[72:73]
	v_fma_f32 v9, -v32, v9, v8
	v_cmp_lt_f32_e64 s[72:73], 0, v9
	v_add_f32_e32 v5, 1.0, v5
	v_rcp_f32_e32 v5, v5
	v_cndmask_b32_e64 v9, v31, v32, s[72:73]
	v_mul_f32_e32 v31, 0x37800000, v9
	v_cndmask_b32_e64 v9, v9, v31, s[68:69]
	ds_read_u16 v31, v21 offset:64
	v_cmp_class_f32_e64 s[68:69], v8, v189
	v_mul_f32_e32 v4, 0x3fb8aa3b, v4
	v_exp_f32_e32 v4, v4
	v_cndmask_b32_e64 v8, v9, v8, s[68:69]
	v_add_f32_e32 v9, 1.0, v10
	v_rcp_f32_e32 v9, v9
	v_mul_f32_e32 v5, v5, v8
	s_waitcnt lgkmcnt(0)
; DI float bf2f(u16 h) { return __uint_as_float(((unsigned)h) << 16); }
; DI float sigmoidf_(float x) { return __builtin_amdgcn_rcpf(1.f + __expf(-x)); }
; DI float softplusf_(float x) { return fmaxf(x, 0.f) + __logf(1.f + __expf(-fabsf(x))); }
; DI void lru1_item(const Params& p, int l, int it, char* smem) {
;     ...
; #pragma unroll
;     for (int n = 0; n < 4; ++n) {
;       f32x4 r = lds_mm<2>(xcs, LP, wid * 16, was, LP, n * 16, f32x4{0.f, 0.f, 0.f, 0.f});
;       f32x4 g = lds_mm<2>(xcs, LP, wid * 16, wxs, LP, n * 16, f32x4{0.f, 0.f, 0.f, 0.f});
;       const int j = n * 16 + fr;
;       const float sp = softplusf_(-lm[j]), bav = ba[j], bxv = bx[j];
; #pragma unroll
;       for (int q = 0; q < 4; ++q) {
;         const int t = wid * 16 + fq * 4 + q;
;         const float rr = sigmoidf_(r[q] + bav), ii = sigmoidf_(g[q] + bxv);
;         const float la = -8.f * rr * sp;
;         const float a = __expf(la);
;         const float x2 = 2.f * la;
;         const float om = (x2 > -0.01f) ? -x2 * (1.f + x2 * (0.5f + x2 * (1.f / 6.f))) : 1.f - __expf(x2);
;         const float u = sqrtf(om) * ii * bf2f(xcs[t * LP + j]);
;         as_[t * 64 + j] = a;
;         us_[t * 64 + j] = u;
;       }
;     }
	v_lshlrev_b32_e32 v8, 16, v31
	v_mul_f32_e32 v5, v5, v8
	v_add_u32_e32 v8, 0x80, v26
	ds_write2st64_b32 v8, v4, v5 offset0:108 offset1:172
	v_mul_f32_e32 v4, 0xc1000000, v9
	v_mul_f32_e32 v4, v28, v4
	v_add_f32_e32 v8, v4, v4
	v_cmp_nlt_f32_e64 s[68:69], s85, v8
	s_and_saveexec_b64 s[10:11], s[68:69]
	s_xor_b64 s[10:11], exec, s[10:11]
	v_mul_f32_e32 v5, 0x3fb8aa3b, v8
	v_exp_f32_e32 v5, v5
	s_nop 0
	v_sub_f32_e32 v5, 1.0, v5
	s_andn2_saveexec_b64 s[10:11], s[10:11]
	s_mov_b32 s20, 0x3e2aaaab
	v_fma_f32 v5, v8, s20, 0.5
	v_fma_f32 v5, v8, v5, 1.0
	v_mul_f32_e64 v5, v5, -v8
	s_or_b64 exec, exec, s[10:11]
	v_mul_f32_e32 v8, 0x4f800000, v5
	v_cmp_gt_f32_e64 s[68:69], s0, v5
	v_add_f32_e32 v6, v6, v126
	v_mul_f32_e32 v6, 0xbfb8aa3b, v6
	v_cndmask_b32_e64 v5, v5, v8, s[68:69]
	v_sqrt_f32_e32 v8, v5
	v_exp_f32_e32 v6, v6
	v_mul_f32_e32 v4, 0x3fb8aa3b, v4
	v_exp_f32_e32 v4, v4
	v_add_u32_e32 v9, -1, v8
	v_fma_f32 v10, -v9, v8, v5
	v_cmp_ge_f32_e64 s[72:73], 0, v10
	v_add_u32_e32 v10, 1, v8
	v_add_f32_e32 v6, 1.0, v6
	v_cndmask_b32_e64 v9, v8, v9, s[72:73]
	v_fma_f32 v8, -v10, v8, v5
	v_cmp_lt_f32_e64 s[72:73], 0, v8
	v_rcp_f32_e32 v6, v6
	s_nop 0
	v_cndmask_b32_e64 v8, v9, v10, s[72:73]
	v_add_f32_e32 v10, v11, v122
	v_mul_f32_e32 v10, 0xbfb8aa3b, v10
	v_exp_f32_e32 v10, v10
	v_mul_f32_e32 v9, 0x37800000, v8
	v_cndmask_b32_e64 v8, v8, v9, s[68:69]
	ds_read_u16 v9, v22 offset:64
	v_cmp_class_f32_e64 s[68:69], v5, v189
	s_nop 1
	v_cndmask_b32_e64 v5, v8, v5, s[68:69]
	v_add_f32_e32 v8, 1.0, v10
	v_rcp_f32_e32 v8, v8
	v_mul_f32_e32 v5, v6, v5
	s_waitcnt lgkmcnt(0)
	v_lshlrev_b32_e32 v6, 16, v9
	v_mul_f32_e32 v5, v5, v6
	v_add_u32_e32 v6, 0x80, v27
	ds_write2st64_b32 v6, v4, v5 offset0:108 offset1:172
	v_mul_f32_e32 v4, 0xc1000000, v8
	v_mul_f32_e32 v4, v28, v4
	v_add_f32_e32 v6, v4, v4
	v_cmp_nlt_f32_e64 s[68:69], s85, v6
	s_and_saveexec_b64 s[10:11], s[68:69]
	s_xor_b64 s[10:11], exec, s[10:11]
	v_mul_f32_e32 v5, 0x3fb8aa3b, v6
	v_exp_f32_e32 v5, v5
	s_nop 0
	v_sub_f32_e32 v5, 1.0, v5
	s_andn2_saveexec_b64 s[10:11], s[10:11]
	s_mov_b32 s20, 0x3e2aaaab
	v_fma_f32 v5, v6, s20, 0.5
	v_fma_f32 v5, v6, v5, 1.0
	v_mul_f32_e64 v5, v5, -v6
	s_or_b64 exec, exec, s[10:11]
	v_add_f32_e32 v6, v7, v126
	v_cmp_gt_f32_e64 s[68:69], s0, v5
	v_mul_f32_e32 v7, 0x4f800000, v5
	v_mul_f32_e32 v6, 0xbfb8aa3b, v6
	v_cndmask_b32_e64 v5, v5, v7, s[68:69]
	v_sqrt_f32_e32 v7, v5
	v_exp_f32_e32 v6, v6
	v_mul_f32_e32 v4, 0x3fb8aa3b, v4
	v_exp_f32_e32 v4, v4
	v_add_u32_e32 v8, -1, v7
	v_fma_f32 v9, -v8, v7, v5
	v_cmp_ge_f32_e64 s[72:73], 0, v9
	v_add_u32_e32 v9, 1, v7
	v_add_f32_e32 v6, 1.0, v6
	v_cndmask_b32_e64 v8, v7, v8, s[72:73]
	v_fma_f32 v7, -v9, v7, v5
	v_cmp_lt_f32_e64 s[72:73], 0, v7
	v_rcp_f32_e32 v6, v6
	v_mov_b32_e32 v36, v185
	v_cndmask_b32_e64 v7, v8, v9, s[72:73]
	ds_read_u16 v9, v24 offset:64
	v_mul_f32_e32 v8, 0x37800000, v7
	v_cndmask_b32_e64 v7, v7, v8, s[68:69]
	v_cmp_class_f32_e64 s[68:69], v5, v189
	s_nop 1
	v_cndmask_b32_e64 v5, v7, v5, s[68:69]
	v_mul_f32_e32 v5, v6, v5
	s_waitcnt lgkmcnt(0)
	v_lshlrev_b32_e32 v6, 16, v9
	v_mul_f32_e32 v5, v5, v6
	v_add_u32_e32 v6, 0x80, v23
	ds_write2st64_b32 v6, v4, v5 offset0:108 offset1:172
	v_mov_b32_e32 v4, v185
	s_nop 0
	v_and_b32_e32 v5, 15, v4
	v_or_b32_e32 v6, v5, v42
	v_mul_lo_u32 v6, v6, s70
	v_and_b32_e32 v4, 48, v4
	v_mul_u32_u24_e32 v5, 0x90, v5
	v_add3_u32 v28, v60, v6, v4
	v_add3_u32 v32, v60, v5, v4
	ds_read_b128 v[4:7], v28
	ds_read_b128 v[8:11], v32 offset:16128
	ds_read_b128 v[28:31], v28 offset:64
	ds_read_b128 v[32:35], v32 offset:16192
	s_nop 0
	v_and_b32_e32 v37, 15, v36
	v_or_b32_e32 v16, v37, v42
	v_and_b32_e32 v36, 48, v36
	v_mul_lo_u32 v16, v16, s70
	v_add3_u32 v62, v60, v16, v36
	ds_read_b128 v[16:19], v62
	s_waitcnt lgkmcnt(3)
	v_mfma_f32_16x16x32_bf16 v[4:7], v[4:7], v[8:11], 0
	v_mul_u32_u24_e32 v8, 0x90, v37
	v_add3_u32 v63, v60, v8, v36
	ds_read_b128 v[36:39], v63 offset:25344
	s_waitcnt lgkmcnt(2)
	v_mfma_f32_16x16x32_bf16 v[8:11], v[28:31], v[32:35], v[4:7]
	ds_read_b128 v[28:31], v63 offset:25408
	s_nop 1
	ds_read_b128 v[4:7], v62 offset:64
	s_waitcnt lgkmcnt(2)
	v_mfma_f32_16x16x32_bf16 v[16:19], v[16:19], v[36:39], 0
	s_waitcnt vmcnt(1)
	s_nop 0
	v_add_f32_e32 v8, v8, v123
	s_waitcnt lgkmcnt(0)
	v_mfma_f32_16x16x32_bf16 v[4:7], v[4:7], v[28:31], v[16:19]
	v_mul_f32_e32 v8, 0xbfb8aa3b, v8
	v_exp_f32_e32 v8, v8
	s_nop 0
	v_mul_f32_e64 v17, |v119|, s90
	v_exp_f32_e32 v17, v17
	v_add_f32_e32 v8, 1.0, v8
	v_rcp_f32_e32 v19, v8
	v_max_f32_e64 v16, -v119, -v119
	v_add_f32_e32 v17, 1.0, v17
	v_cmp_gt_f32_e64 s[68:69], s1, v17
	v_max_f32_e32 v16, 0, v16
	s_nop 0
	v_cndmask_b32_e64 v18, 0, 32, s[68:69]
	v_ldexp_f32 v17, v17, v18
	v_log_f32_e32 v17, v17
	v_cndmask_b32_e64 v18, 0, v213, s[68:69]
	v_mul_f32_e32 v8, 0x3f317217, v17
	v_fma_f32 v8, v17, s91, -v8
	v_fmac_f32_e32 v8, 0x3377d1cf, v17
	v_cmp_lt_f32_e64 s[68:69], |v17|, s84
	v_fmac_f32_e32 v8, 0x3f317217, v17
	s_nop 0
	v_cndmask_b32_e64 v8, v17, v8, s[68:69]
	v_sub_f32_e32 v8, v8, v18
	v_add_f32_e32 v8, v16, v8
	v_mul_f32_e32 v16, 0xc1000000, v19
	v_mul_f32_e32 v16, v8, v16
	v_add_f32_e32 v18, v16, v16
	v_cmp_nlt_f32_e64 s[68:69], s85, v18
	s_and_saveexec_b64 s[10:11], s[68:69]
	s_xor_b64 s[10:11], exec, s[10:11]
	v_mul_f32_e32 v17, 0x3fb8aa3b, v18
	v_exp_f32_e32 v17, v17
	s_nop 0
	v_sub_f32_e32 v17, 1.0, v17
	s_andn2_saveexec_b64 s[10:11], s[10:11]
	s_mov_b32 s20, 0x3e2aaaab
	v_fma_f32 v17, v18, s20, 0.5
	v_fma_f32 v17, v18, v17, 1.0
	v_mul_f32_e64 v17, v17, -v18
	s_or_b64 exec, exec, s[10:11]
	v_mul_f32_e32 v18, 0x4f800000, v17
	v_cmp_gt_f32_e64 s[68:69], s0, v17
	s_waitcnt vmcnt(0)
; DI float bf2f(u16 h) { return __uint_as_float(((unsigned)h) << 16); }
; DI float sigmoidf_(float x) { return __builtin_amdgcn_rcpf(1.f + __expf(-x)); }
; DI float softplusf_(float x) { return fmaxf(x, 0.f) + __logf(1.f + __expf(-fabsf(x))); }
; DI void lru1_item(const Params& p, int l, int it, char* smem) {
;     ...
; #pragma unroll
;     for (int n = 0; n < 4; ++n) {
;       f32x4 r = lds_mm<2>(xcs, LP, wid * 16, was, LP, n * 16, f32x4{0.f, 0.f, 0.f, 0.f});
;       f32x4 g = lds_mm<2>(xcs, LP, wid * 16, wxs, LP, n * 16, f32x4{0.f, 0.f, 0.f, 0.f});
;       const int j = n * 16 + fr;
;       const float sp = softplusf_(-lm[j]), bav = ba[j], bxv = bx[j];
; #pragma unroll
;       for (int q = 0; q < 4; ++q) {
;         const int t = wid * 16 + fq * 4 + q;
;         const float rr = sigmoidf_(r[q] + bav), ii = sigmoidf_(g[q] + bxv);
;         const float la = -8.f * rr * sp;
;         const float a = __expf(la);
;         const float x2 = 2.f * la;
;         const float om = (x2 > -0.01f) ? -x2 * (1.f + x2 * (0.5f + x2 * (1.f / 6.f))) : 1.f - __expf(x2);
;         const float u = sqrtf(om) * ii * bf2f(xcs[t * LP + j]);
;         as_[t * 64 + j] = a;
;         us_[t * 64 + j] = u;
;       }
;     }
;   }
;   __syncthreads();
	v_add_f32_e32 v4, v4, v127
	v_mul_f32_e32 v4, 0xbfb8aa3b, v4
	v_cndmask_b32_e64 v17, v17, v18, s[68:69]
	v_sqrt_f32_e32 v18, v17
	v_exp_f32_e32 v4, v4
	v_add_f32_e32 v9, v9, v123
	v_mul_f32_e32 v9, 0xbfb8aa3b, v9
	v_add_u32_e32 v19, -1, v18
	v_fma_f32 v28, -v19, v18, v17
	v_cmp_ge_f32_e64 s[72:73], 0, v28
	v_add_u32_e32 v28, 1, v18
	v_exp_f32_e32 v9, v9
	v_cndmask_b32_e64 v19, v18, v19, s[72:73]
	v_fma_f32 v18, -v28, v18, v17
	v_add_f32_e32 v4, 1.0, v4
	v_cmp_lt_f32_e64 s[72:73], 0, v18
	ds_read_u16 v13, v13 offset:96
	v_rcp_f32_e32 v4, v4
	v_cndmask_b32_e64 v18, v19, v28, s[72:73]
	v_mul_f32_e32 v16, 0x3fb8aa3b, v16
	v_mul_f32_e32 v19, 0x37800000, v18
	v_add_f32_e32 v9, 1.0, v9
	v_exp_f32_e32 v16, v16
	v_cndmask_b32_e64 v18, v18, v19, s[68:69]
	v_cmp_class_f32_e64 s[68:69], v17, v189
	v_rcp_f32_e32 v9, v9
	s_waitcnt lgkmcnt(0)
	v_lshlrev_b32_e32 v13, 16, v13
	v_cndmask_b32_e64 v17, v18, v17, s[68:69]
	v_mul_f32_e32 v4, v4, v17
	v_mul_f32_e32 v4, v4, v13
	v_add_u32_e32 v13, 0xc0, v25
	ds_write2st64_b32 v13, v16, v4 offset0:108 offset1:172
	v_mul_f32_e32 v4, 0xc1000000, v9
	v_mul_f32_e32 v4, v8, v4
	v_add_f32_e32 v13, v4, v4
	v_cmp_nlt_f32_e64 s[68:69], s85, v13
	s_and_saveexec_b64 s[10:11], s[68:69]
	s_xor_b64 s[10:11], exec, s[10:11]
	v_mul_f32_e32 v9, 0x3fb8aa3b, v13
	v_exp_f32_e32 v9, v9
	s_nop 0
	v_sub_f32_e32 v9, 1.0, v9
	s_andn2_saveexec_b64 s[10:11], s[10:11]
	s_mov_b32 s20, 0x3e2aaaab
	v_fma_f32 v9, v13, s20, 0.5
	v_fma_f32 v9, v13, v9, 1.0
	v_mul_f32_e64 v9, v9, -v13
	s_or_b64 exec, exec, s[10:11]
	v_mul_f32_e32 v13, 0x4f800000, v9
	v_cmp_gt_f32_e64 s[68:69], s0, v9
	v_add_f32_e32 v5, v5, v127
	v_mul_f32_e32 v5, 0xbfb8aa3b, v5
	v_cndmask_b32_e64 v9, v9, v13, s[68:69]
	v_sqrt_f32_e32 v13, v9
	v_exp_f32_e32 v5, v5
	v_add_f32_e32 v10, v10, v123
	v_mul_f32_e32 v10, 0xbfb8aa3b, v10
	v_add_u32_e32 v16, -1, v13
	v_fma_f32 v17, -v16, v13, v9
	v_cmp_ge_f32_e64 s[72:73], 0, v17
	v_add_u32_e32 v17, 1, v13
	v_exp_f32_e32 v10, v10
	v_cndmask_b32_e64 v16, v13, v16, s[72:73]
	v_fma_f32 v13, -v17, v13, v9
	v_cmp_lt_f32_e64 s[72:73], 0, v13
	v_add_f32_e32 v5, 1.0, v5
	v_rcp_f32_e32 v5, v5
	v_cndmask_b32_e64 v13, v16, v17, s[72:73]
	v_mul_f32_e32 v16, 0x37800000, v13
	v_cndmask_b32_e64 v13, v13, v16, s[68:69]
	ds_read_u16 v16, v21 offset:96
	v_mul_f32_e32 v4, 0x3fb8aa3b, v4
	v_add_f32_e32 v10, 1.0, v10
	v_exp_f32_e32 v4, v4
	v_cmp_class_f32_e64 s[68:69], v9, v189
	v_rcp_f32_e32 v10, v10
	s_nop 0
	v_cndmask_b32_e64 v9, v13, v9, s[68:69]
	v_mul_f32_e32 v5, v5, v9
	s_waitcnt lgkmcnt(0)
	v_lshlrev_b32_e32 v9, 16, v16
	v_mul_f32_e32 v5, v5, v9
	v_add_u32_e32 v9, 0xc0, v26
	ds_write2st64_b32 v9, v4, v5 offset0:108 offset1:172
	v_mul_f32_e32 v4, 0xc1000000, v10
	v_mul_f32_e32 v4, v8, v4
	v_add_f32_e32 v9, v4, v4
	v_cmp_nlt_f32_e64 s[68:69], s85, v9
	s_and_saveexec_b64 s[10:11], s[68:69]
	s_xor_b64 s[10:11], exec, s[10:11]
	v_mul_f32_e32 v5, 0x3fb8aa3b, v9
	v_exp_f32_e32 v5, v5
	s_nop 0
	v_sub_f32_e32 v5, 1.0, v5
	s_andn2_saveexec_b64 s[10:11], s[10:11]
	s_mov_b32 s20, 0x3e2aaaab
	v_fma_f32 v5, v9, s20, 0.5
	v_fma_f32 v5, v9, v5, 1.0
	v_mul_f32_e64 v5, v5, -v9
	s_or_b64 exec, exec, s[10:11]
	v_mul_f32_e32 v9, 0x4f800000, v5
	v_cmp_gt_f32_e64 s[68:69], s0, v5
	v_add_f32_e32 v6, v6, v127
	v_mul_f32_e32 v6, 0xbfb8aa3b, v6
	v_cndmask_b32_e64 v5, v5, v9, s[68:69]
	v_sqrt_f32_e32 v9, v5
	v_exp_f32_e32 v6, v6
	v_add_f32_e32 v11, v11, v123
	v_mul_f32_e32 v11, 0xbfb8aa3b, v11
	v_add_u32_e32 v10, -1, v9
	v_fma_f32 v13, -v10, v9, v5
	v_cmp_ge_f32_e64 s[72:73], 0, v13
	v_add_u32_e32 v13, 1, v9
	v_exp_f32_e32 v11, v11
	v_cndmask_b32_e64 v10, v9, v10, s[72:73]
	v_fma_f32 v9, -v13, v9, v5
	v_cmp_lt_f32_e64 s[72:73], 0, v9
	v_add_f32_e32 v6, 1.0, v6
	v_rcp_f32_e32 v6, v6
	v_cndmask_b32_e64 v9, v10, v13, s[72:73]
	v_mul_f32_e32 v10, 0x37800000, v9
	v_cndmask_b32_e64 v9, v9, v10, s[68:69]
	ds_read_u16 v10, v22 offset:96
	v_cmp_class_f32_e64 s[68:69], v5, v189
	v_mul_f32_e32 v4, 0x3fb8aa3b, v4
	v_exp_f32_e32 v4, v4
	v_cndmask_b32_e64 v5, v9, v5, s[68:69]
	v_add_f32_e32 v9, 1.0, v11
	v_rcp_f32_e32 v9, v9
	v_mul_f32_e32 v5, v6, v5
	s_waitcnt lgkmcnt(0)
	v_lshlrev_b32_e32 v6, 16, v10
	v_mul_f32_e32 v5, v5, v6
	v_add_u32_e32 v6, 0xc0, v27
	ds_write2st64_b32 v6, v4, v5 offset0:108 offset1:172
	v_mul_f32_e32 v4, 0xc1000000, v9
	v_mul_f32_e32 v4, v8, v4
	v_add_f32_e32 v6, v4, v4
	v_cmp_nlt_f32_e64 s[68:69], s85, v6
	s_and_saveexec_b64 s[10:11], s[68:69]
	s_xor_b64 s[10:11], exec, s[10:11]
	v_mul_f32_e32 v5, 0x3fb8aa3b, v6
	v_exp_f32_e32 v5, v5
	s_nop 0
	v_sub_f32_e32 v5, 1.0, v5
	s_andn2_saveexec_b64 s[10:11], s[10:11]
	s_mov_b32 s20, 0x3e2aaaab
	v_fma_f32 v5, v6, s20, 0.5
	v_fma_f32 v5, v6, v5, 1.0
	v_mul_f32_e64 v5, v5, -v6
	s_or_b64 exec, exec, s[10:11]
	v_add_f32_e32 v6, v7, v127
	v_mul_f32_e32 v7, 0x4f800000, v5
	v_cmp_gt_f32_e64 s[68:69], s0, v5
	v_mul_f32_e32 v6, 0xbfb8aa3b, v6
	v_exp_f32_e32 v6, v6
	v_cndmask_b32_e64 v5, v5, v7, s[68:69]
	v_sqrt_f32_e32 v7, v5
	v_mul_f32_e32 v4, 0x3fb8aa3b, v4
	v_add_f32_e32 v6, 1.0, v6
	v_rcp_f32_e32 v6, v6
	v_add_u32_e32 v8, -1, v7
	v_fma_f32 v9, -v8, v7, v5
	v_cmp_ge_f32_e64 s[72:73], 0, v9
	v_add_u32_e32 v9, 1, v7
	v_exp_f32_e32 v4, v4
	v_cndmask_b32_e64 v8, v7, v8, s[72:73]
	v_fma_f32 v7, -v9, v7, v5
	v_cmp_lt_f32_e64 s[72:73], 0, v7
	v_lshlrev_b32_e32 v13, 2, v20
	v_mov_b32_e32 v61, 1.0
	v_cndmask_b32_e64 v7, v8, v9, s[72:73]
	ds_read_u16 v9, v24 offset:96
	v_mul_f32_e32 v8, 0x37800000, v7
	v_cndmask_b32_e64 v7, v7, v8, s[68:69]
	v_cmp_class_f32_e64 s[68:69], v5, v189
	v_lshl_add_u32 v43, v43, 2, v60
	s_nop 0
	v_cndmask_b32_e64 v5, v7, v5, s[68:69]
	v_mul_f32_e32 v5, v6, v5
	s_waitcnt lgkmcnt(0)
	v_lshlrev_b32_e32 v6, 16, v9
	v_mul_f32_e32 v5, v5, v6
	v_add_u32_e32 v6, 0xc0, v23
	ds_write2st64_b32 v6, v4, v5 offset0:108 offset1:172
	v_lshl_or_b32 v4, v12, 12, v13
	v_add_u32_e32 v4, v60, v4
	s_waitcnt lgkmcnt(0)
	s_barrier
; DI void lru1_item(const Params& p, int l, int it, char* smem) {
;     ...
;   {
;     float av[16], uv[16];
; #pragma unroll
;     for (int k = 0; k < 16; ++k) { av[k] = as_[(tq * 16 + k) * 64 + i]; uv[k] = us_[(tq * 16 + k) * 64 + i]; }
;     float P = 1.f, hh = 0.f;
; #pragma unroll
;     for (int k = 0; k < 16; ++k) { P *= av[k]; hh = av[k] * hh + uv[k]; }
;     segP[tq * 64 + i] = P; segH[tq * 64 + i] = hh;
;     __syncthreads();
;     float Pin = 1.f, hin = 0.f;
;     for (int g = 0; g < tq; ++g) { const float pg = segP[g * 64 + i], hg = segH[g * 64 + i]; hin = pg * hin + hg; Pin *= pg; }
	ds_read2st64_b32 v[38:39], v4 offset0:108 offset1:109
	ds_read2st64_b32 v[34:35], v4 offset0:110 offset1:111
	ds_read2st64_b32 v[30:31], v4 offset0:112 offset1:113
	ds_read2st64_b32 v[26:27], v4 offset0:114 offset1:115
	ds_read2st64_b32 v[36:37], v4 offset0:172 offset1:173
	ds_read2st64_b32 v[32:33], v4 offset0:174 offset1:175
	ds_read2st64_b32 v[28:29], v4 offset0:176 offset1:177
	ds_read2st64_b32 v[24:25], v4 offset0:178 offset1:179
	ds_read2st64_b32 v[22:23], v4 offset0:116 offset1:117
	ds_read2st64_b32 v[16:17], v4 offset0:118 offset1:119
	ds_read2st64_b32 v[10:11], v4 offset0:120 offset1:121
	ds_read2st64_b32 v[6:7], v4 offset0:122 offset1:123
	ds_read2st64_b32 v[20:21], v4 offset0:180 offset1:181
	ds_read2st64_b32 v[14:15], v4 offset0:182 offset1:183
	ds_read2st64_b32 v[8:9], v4 offset0:184 offset1:185
	ds_read2st64_b32 v[4:5], v4 offset0:186 offset1:187
	s_waitcnt lgkmcnt(11)
	v_fma_f32 v62, 0, v38, v36
	v_mul_f32_e32 v18, v38, v39
	v_fma_f32 v19, v62, v39, v37
	v_mul_f32_e32 v18, v18, v34
	s_waitcnt lgkmcnt(10)
	v_fma_f32 v19, v19, v34, v32
	v_mul_f32_e32 v18, v18, v35
	v_fma_f32 v19, v19, v35, v33
	v_mul_f32_e32 v18, v18, v30
	s_waitcnt lgkmcnt(9)
	v_fma_f32 v19, v19, v30, v28
	v_mul_f32_e32 v18, v18, v31
	v_fma_f32 v19, v19, v31, v29
	v_mul_f32_e32 v18, v18, v26
	s_waitcnt lgkmcnt(8)
	v_fma_f32 v19, v19, v26, v24
	v_mul_f32_e32 v18, v18, v27
	v_fma_f32 v19, v19, v27, v25
	s_waitcnt lgkmcnt(7)
	v_mul_f32_e32 v18, v18, v22
	s_waitcnt lgkmcnt(3)
	v_fma_f32 v19, v19, v22, v20
	v_mul_f32_e32 v18, v18, v23
	v_fma_f32 v19, v19, v23, v21
	v_mul_f32_e32 v18, v18, v16
	s_waitcnt lgkmcnt(2)
	v_fma_f32 v19, v19, v16, v14
	v_mul_f32_e32 v18, v18, v17
	v_fma_f32 v19, v19, v17, v15
	v_mul_f32_e32 v18, v18, v10
	s_waitcnt lgkmcnt(1)
	v_fma_f32 v19, v19, v10, v8
	v_mul_f32_e32 v18, v18, v11
	v_fma_f32 v19, v19, v11, v9
	v_mul_f32_e32 v18, v18, v6
	s_waitcnt lgkmcnt(0)
	v_fma_f32 v19, v19, v6, v4
	v_mul_f32_e32 v18, v18, v7
	v_fma_f32 v19, v19, v7, v5
	v_cmp_lt_i32_e64 s[68:69], 0, v12
	ds_write2st64_b32 v43, v18, v19 offset0:236 offset1:240
	s_waitcnt lgkmcnt(0)
	s_barrier
	s_and_saveexec_b64 s[72:73], s[68:69]
	s_cbranch_execz .LBB0_1682
	v_mul_i32_i24_e32 v18, 0x12000, v59
	v_readlane_b32 s10, v253, 62
	v_mov_b32_e32 v61, 1.0
	v_mov_b32_e32 v19, 0
	v_add3_u32 v13, v18, v13, s10
	s_mov_b64 s[74:75], 0
